# GEMM k-loops: LDS-DMA uses the scalar-base address form (8 fewer VALU adds per iteration) and the vmcnt/lgkmcnt waits before each barrier are one instruction
# speedup vs baseline: 1.0059x; 1.0002x over previous
.LBB0_259:
	ds_read_b128 v[152:155], v149
	ds_read_b128 v[156:159], v149 offset:1024
	ds_read_b128 v[160:163], v149 offset:2048
	ds_read_b128 v[164:167], v149 offset:3072
	ds_read_b128 v[168:171], v150
	ds_read_b128 v[172:175], v150 offset:1024
	ds_read_b128 v[176:179], v150 offset:2048
	ds_read_b128 v[184:187], v150 offset:3072
	s_add_u32 s24, s22, 0xfffc0080
	s_addc_u32 s25, s23, -1
	s_cmp_eq_u32 s51, 12
	s_cselect_b32 s27, s15, s25
	s_cselect_b32 s26, s47, s24
	s_cselect_b32 s25, s13, s50
	s_cselect_b32 s24, s48, s49
	s_add_i32 m0, s21, 0xc000
	ds_read_b128 v[188:191], v151
	ds_read_b128 v[192:195], v151 offset:1024
	ds_read_b128 v[196:199], v151 offset:2048
	ds_read_b128 v[200:203], v151 offset:3072
	ds_read_b128 v[204:207], v151 offset:4096
	ds_read_b128 v[208:211], v151 offset:5120
	ds_read_b128 v[212:215], v151 offset:6144
	ds_read_b128 v[216:219], v151 offset:7168
	global_load_lds_dwordx4 v136, s[22:23]
	s_add_i32 m0, s21, 0xe000
	s_nop 0
	global_load_lds_dwordx4 v138, s[22:23]
	s_waitcnt vmcnt(8) lgkmcnt(0)
	s_barrier
	s_setprio 1
	v_mfma_f32_16x16x32_bf16 v[124:127], v[152:155], v[188:191], v[124:127]
	v_mfma_f32_16x16x32_bf16 v[120:123], v[160:163], v[188:191], v[120:123]
	v_mfma_f32_16x16x32_bf16 v[108:111], v[152:155], v[196:199], v[108:111]
	v_mfma_f32_16x16x32_bf16 v[104:107], v[160:163], v[196:199], v[104:107]
	v_mfma_f32_16x16x32_bf16 v[92:95], v[152:155], v[204:207], v[92:95]
	v_mfma_f32_16x16x32_bf16 v[88:91], v[160:163], v[204:207], v[88:91]
	v_mfma_f32_16x16x32_bf16 v[76:79], v[152:155], v[212:215], v[76:79]
	v_mfma_f32_16x16x32_bf16 v[72:75], v[160:163], v[212:215], v[72:75]
	v_mfma_f32_16x16x32_bf16 v[124:127], v[156:159], v[192:195], v[124:127]
	v_mfma_f32_16x16x32_bf16 v[120:123], v[164:167], v[192:195], v[120:123]
	v_mfma_f32_16x16x32_bf16 v[108:111], v[156:159], v[200:203], v[108:111]
	v_mfma_f32_16x16x32_bf16 v[104:107], v[164:167], v[200:203], v[104:107]
	v_mfma_f32_16x16x32_bf16 v[92:95], v[156:159], v[208:211], v[92:95]
	v_mfma_f32_16x16x32_bf16 v[88:91], v[164:167], v[208:211], v[88:91]
	v_mfma_f32_16x16x32_bf16 v[76:79], v[156:159], v[216:219], v[76:79]
	v_mfma_f32_16x16x32_bf16 v[72:75], v[164:167], v[216:219], v[72:75]
	v_mfma_f32_16x16x32_bf16 v[116:119], v[168:171], v[188:191], v[116:119]
	v_mfma_f32_16x16x32_bf16 v[112:115], v[176:179], v[188:191], v[112:115]
	v_mfma_f32_16x16x32_bf16 v[100:103], v[168:171], v[196:199], v[100:103]
	v_mfma_f32_16x16x32_bf16 v[96:99], v[176:179], v[196:199], v[96:99]
	v_mfma_f32_16x16x32_bf16 v[84:87], v[168:171], v[204:207], v[84:87]
	v_mfma_f32_16x16x32_bf16 v[80:83], v[176:179], v[204:207], v[80:83]
	v_mfma_f32_16x16x32_bf16 v[68:71], v[168:171], v[212:215], v[68:71]
	v_mfma_f32_16x16x32_bf16 v[64:67], v[176:179], v[212:215], v[64:67]
	v_mfma_f32_16x16x32_bf16 v[116:119], v[172:175], v[192:195], v[116:119]
	v_mfma_f32_16x16x32_bf16 v[112:115], v[184:187], v[192:195], v[112:115]
	v_mfma_f32_16x16x32_bf16 v[100:103], v[172:175], v[200:203], v[100:103]
	v_mfma_f32_16x16x32_bf16 v[96:99], v[184:187], v[200:203], v[96:99]
	v_mfma_f32_16x16x32_bf16 v[84:87], v[172:175], v[208:211], v[84:87]
	v_mfma_f32_16x16x32_bf16 v[80:83], v[184:187], v[208:211], v[80:83]
	v_mfma_f32_16x16x32_bf16 v[68:71], v[172:175], v[216:219], v[68:71]
	v_mfma_f32_16x16x32_bf16 v[64:67], v[184:187], v[216:219], v[64:67]
	s_setprio 0
	s_barrier
	s_add_i32 s52, s43, s34
	v_lshl_add_u64 v[144:145], s[24:25], 0, v[130:131]
	s_mov_b32 m0, s52
	ds_read_b128 v[188:191], v151 offset:16384
	ds_read_b128 v[192:195], v151 offset:17408
	ds_read_b128 v[196:199], v151 offset:18432
	ds_read_b128 v[200:203], v151 offset:19456
	ds_read_b128 v[204:207], v151 offset:20480
	ds_read_b128 v[208:211], v151 offset:21504
	ds_read_b128 v[212:215], v151 offset:22528
	ds_read_b128 v[216:219], v151 offset:23552
	global_load_lds_dwordx4 v[144:145], off
	s_add_i32 m0, s52, 0x2000
	s_add_u32 s52, s24, 0x40000
	v_lshl_add_u64 v[180:181], s[24:25], 0, v[134:135]
	s_addc_u32 s53, s25, 0
	s_add_i32 s54, s44, s34
	global_load_lds_dwordx4 v[180:181], off
	s_mov_b32 m0, s54
	v_lshl_add_u64 v[222:223], s[26:27], 0, v[132:133]
	global_load_lds_dwordx4 v130, s[52:53]
	s_add_i32 m0, s54, 0x2000
	s_nop 0
	global_load_lds_dwordx4 v134, s[52:53]
	v_lshl_add_u64 v[220:221], s[26:27], 0, v[128:129]
	s_mov_b32 m0, s21
	s_nop 0
	global_load_lds_dwordx4 v[220:221], off
	s_mov_b32 m0, s36
	s_nop 0
	global_load_lds_dwordx4 v[222:223], off
	s_waitcnt vmcnt(8) lgkmcnt(0)
	s_barrier
	s_setprio 1
	v_mfma_f32_16x16x32_bf16 v[60:63], v[152:155], v[188:191], v[60:63]
	v_mfma_f32_16x16x32_bf16 v[56:59], v[160:163], v[188:191], v[56:59]
	v_mfma_f32_16x16x32_bf16 v[44:47], v[152:155], v[196:199], v[44:47]
	v_mfma_f32_16x16x32_bf16 v[40:43], v[160:163], v[196:199], v[40:43]
	v_mfma_f32_16x16x32_bf16 v[28:31], v[152:155], v[204:207], v[28:31]
	v_mfma_f32_16x16x32_bf16 v[24:27], v[160:163], v[204:207], v[24:27]
	v_mfma_f32_16x16x32_bf16 v[12:15], v[152:155], v[212:215], v[12:15]
	v_mfma_f32_16x16x32_bf16 v[8:11], v[160:163], v[212:215], v[8:11]
	v_mfma_f32_16x16x32_bf16 v[60:63], v[156:159], v[192:195], v[60:63]
	v_mfma_f32_16x16x32_bf16 v[56:59], v[164:167], v[192:195], v[56:59]
	v_mfma_f32_16x16x32_bf16 v[44:47], v[156:159], v[200:203], v[44:47]
	v_mfma_f32_16x16x32_bf16 v[40:43], v[164:167], v[200:203], v[40:43]
	v_mfma_f32_16x16x32_bf16 v[28:31], v[156:159], v[208:211], v[28:31]
	v_mfma_f32_16x16x32_bf16 v[24:27], v[164:167], v[208:211], v[24:27]
	v_mfma_f32_16x16x32_bf16 v[12:15], v[156:159], v[216:219], v[12:15]
	v_mfma_f32_16x16x32_bf16 v[8:11], v[164:167], v[216:219], v[8:11]
	v_mfma_f32_16x16x32_bf16 v[52:55], v[168:171], v[188:191], v[52:55]
	v_mfma_f32_16x16x32_bf16 v[48:51], v[176:179], v[188:191], v[48:51]
	v_mfma_f32_16x16x32_bf16 v[36:39], v[168:171], v[196:199], v[36:39]
	v_mfma_f32_16x16x32_bf16 v[32:35], v[176:179], v[196:199], v[32:35]
	v_mfma_f32_16x16x32_bf16 v[20:23], v[168:171], v[204:207], v[20:23]
	v_mfma_f32_16x16x32_bf16 v[16:19], v[176:179], v[204:207], v[16:19]
	v_mfma_f32_16x16x32_bf16 v[4:7], v[168:171], v[212:215], v[4:7]
	v_mfma_f32_16x16x32_bf16 v[0:3], v[176:179], v[212:215], v[0:3]
	v_mfma_f32_16x16x32_bf16 v[52:55], v[172:175], v[192:195], v[52:55]
	v_mfma_f32_16x16x32_bf16 v[48:51], v[184:187], v[192:195], v[48:51]
	v_mfma_f32_16x16x32_bf16 v[36:39], v[172:175], v[200:203], v[36:39]
	v_mfma_f32_16x16x32_bf16 v[32:35], v[184:187], v[200:203], v[32:35]
	v_mfma_f32_16x16x32_bf16 v[20:23], v[172:175], v[208:211], v[20:23]
	v_mfma_f32_16x16x32_bf16 v[16:19], v[184:187], v[208:211], v[16:19]
	v_mfma_f32_16x16x32_bf16 v[4:7], v[172:175], v[216:219], v[4:7]
	v_mfma_f32_16x16x32_bf16 v[0:3], v[184:187], v[216:219], v[0:3]
	s_setprio 0
	s_barrier
	s_add_i32 s52, 0, 0x18000
	s_add_i32 s53, 0, 0x1c000
	v_add_u32_e32 v164, s52, v147
	v_add_u32_e32 v183, s53, v147
	ds_read_b128 v[152:155], v164
	ds_read_b128 v[156:159], v164 offset:1024
	ds_read_b128 v[160:163], v164 offset:2048
	ds_read_b128 v[164:167], v164 offset:3072
	ds_read_b128 v[168:171], v183
	ds_read_b128 v[172:175], v183 offset:1024
	ds_read_b128 v[176:179], v183 offset:2048
	ds_read_b128 v[184:187], v183 offset:3072
	s_add_u32 s26, s26, 0x40000
	s_addc_u32 s27, s27, 0
	s_mov_b32 m0, s37
	ds_read_b128 v[188:191], v151 offset:32768
	ds_read_b128 v[192:195], v151 offset:33792
	ds_read_b128 v[196:199], v151 offset:34816
	ds_read_b128 v[200:203], v151 offset:35840
	ds_read_b128 v[204:207], v151 offset:36864
	ds_read_b128 v[208:211], v151 offset:37888
	ds_read_b128 v[212:215], v151 offset:38912
	ds_read_b128 v[216:219], v151 offset:39936
	global_load_lds_dwordx4 v128, s[26:27]
	s_mov_b32 m0, s38
	s_nop 0
	global_load_lds_dwordx4 v132, s[26:27]
	s_waitcnt vmcnt(8) lgkmcnt(0)
	s_barrier
	s_setprio 1
	v_mfma_f32_16x16x32_bf16 v[124:127], v[152:155], v[188:191], v[124:127]
	v_mfma_f32_16x16x32_bf16 v[120:123], v[160:163], v[188:191], v[120:123]
	v_mfma_f32_16x16x32_bf16 v[108:111], v[152:155], v[196:199], v[108:111]
	v_mfma_f32_16x16x32_bf16 v[104:107], v[160:163], v[196:199], v[104:107]
	v_mfma_f32_16x16x32_bf16 v[92:95], v[152:155], v[204:207], v[92:95]
	v_mfma_f32_16x16x32_bf16 v[88:91], v[160:163], v[204:207], v[88:91]
	v_mfma_f32_16x16x32_bf16 v[76:79], v[152:155], v[212:215], v[76:79]
	v_mfma_f32_16x16x32_bf16 v[72:75], v[160:163], v[212:215], v[72:75]
	v_mfma_f32_16x16x32_bf16 v[124:127], v[156:159], v[192:195], v[124:127]
	v_mfma_f32_16x16x32_bf16 v[120:123], v[164:167], v[192:195], v[120:123]
	v_mfma_f32_16x16x32_bf16 v[108:111], v[156:159], v[200:203], v[108:111]
	v_mfma_f32_16x16x32_bf16 v[104:107], v[164:167], v[200:203], v[104:107]
	v_mfma_f32_16x16x32_bf16 v[92:95], v[156:159], v[208:211], v[92:95]
	v_mfma_f32_16x16x32_bf16 v[88:91], v[164:167], v[208:211], v[88:91]
	v_mfma_f32_16x16x32_bf16 v[76:79], v[156:159], v[216:219], v[76:79]
	v_mfma_f32_16x16x32_bf16 v[72:75], v[164:167], v[216:219], v[72:75]
	v_mfma_f32_16x16x32_bf16 v[116:119], v[168:171], v[188:191], v[116:119]
	v_mfma_f32_16x16x32_bf16 v[112:115], v[176:179], v[188:191], v[112:115]
	v_mfma_f32_16x16x32_bf16 v[100:103], v[168:171], v[196:199], v[100:103]
	v_mfma_f32_16x16x32_bf16 v[96:99], v[176:179], v[196:199], v[96:99]
	v_mfma_f32_16x16x32_bf16 v[84:87], v[168:171], v[204:207], v[84:87]
	v_mfma_f32_16x16x32_bf16 v[80:83], v[176:179], v[204:207], v[80:83]
	v_mfma_f32_16x16x32_bf16 v[68:71], v[168:171], v[212:215], v[68:71]
	v_mfma_f32_16x16x32_bf16 v[64:67], v[176:179], v[212:215], v[64:67]
	v_mfma_f32_16x16x32_bf16 v[116:119], v[172:175], v[192:195], v[116:119]
	v_mfma_f32_16x16x32_bf16 v[112:115], v[184:187], v[192:195], v[112:115]
	v_mfma_f32_16x16x32_bf16 v[100:103], v[172:175], v[200:203], v[100:103]
	v_mfma_f32_16x16x32_bf16 v[96:99], v[184:187], v[200:203], v[96:99]
	v_mfma_f32_16x16x32_bf16 v[84:87], v[172:175], v[208:211], v[84:87]
	v_mfma_f32_16x16x32_bf16 v[80:83], v[184:187], v[208:211], v[80:83]
	v_mfma_f32_16x16x32_bf16 v[68:71], v[172:175], v[216:219], v[68:71]
	v_mfma_f32_16x16x32_bf16 v[64:67], v[184:187], v[216:219], v[64:67]
	s_setprio 0
	s_barrier
	s_add_i32 s26, s52, s34
	v_lshl_add_u64 v[144:145], v[144:145], 0, s[8:9]
	s_mov_b32 m0, s26
	ds_read_b128 v[188:191], v151 offset:49152
	ds_read_b128 v[192:195], v151 offset:50176
	ds_read_b128 v[196:199], v151 offset:51200
	ds_read_b128 v[200:203], v151 offset:52224
	ds_read_b128 v[204:207], v151 offset:53248
	ds_read_b128 v[208:211], v151 offset:54272
	ds_read_b128 v[212:215], v151 offset:55296
	ds_read_b128 v[216:219], v151 offset:56320
	global_load_lds_dwordx4 v[144:145], off
	s_add_i32 m0, s26, 0x2000
	s_add_u32 s24, s24, 0x40080
	v_lshl_add_u64 v[144:145], v[180:181], 0, s[8:9]
	s_addc_u32 s25, s25, 0
	s_add_i32 s26, s53, s34
	global_load_lds_dwordx4 v[144:145], off
	s_mov_b32 m0, s26
	s_nop 0
	global_load_lds_dwordx4 v130, s[24:25]
	s_add_i32 m0, s26, 0x2000
	s_nop 0
	global_load_lds_dwordx4 v134, s[24:25]
	v_lshl_add_u64 v[144:145], v[220:221], 0, s[8:9]
	s_mov_b32 m0, s41
	s_nop 0
	global_load_lds_dwordx4 v[144:145], off
	v_lshl_add_u64 v[144:145], v[222:223], 0, s[8:9]
	s_mov_b32 m0, s42
	s_nop 0
	global_load_lds_dwordx4 v[144:145], off
	s_waitcnt vmcnt(8) lgkmcnt(0)
	s_barrier
	s_setprio 1
	v_mfma_f32_16x16x32_bf16 v[60:63], v[152:155], v[188:191], v[60:63]
	v_mfma_f32_16x16x32_bf16 v[56:59], v[160:163], v[188:191], v[56:59]
	v_mfma_f32_16x16x32_bf16 v[44:47], v[152:155], v[196:199], v[44:47]
	v_mfma_f32_16x16x32_bf16 v[40:43], v[160:163], v[196:199], v[40:43]
	v_mfma_f32_16x16x32_bf16 v[28:31], v[152:155], v[204:207], v[28:31]
	v_mfma_f32_16x16x32_bf16 v[24:27], v[160:163], v[204:207], v[24:27]
	v_mfma_f32_16x16x32_bf16 v[12:15], v[152:155], v[212:215], v[12:15]
	v_mfma_f32_16x16x32_bf16 v[8:11], v[160:163], v[212:215], v[8:11]
	v_mfma_f32_16x16x32_bf16 v[60:63], v[156:159], v[192:195], v[60:63]
	v_mfma_f32_16x16x32_bf16 v[56:59], v[164:167], v[192:195], v[56:59]
	v_mfma_f32_16x16x32_bf16 v[44:47], v[156:159], v[200:203], v[44:47]
	v_mfma_f32_16x16x32_bf16 v[40:43], v[164:167], v[200:203], v[40:43]
	v_mfma_f32_16x16x32_bf16 v[28:31], v[156:159], v[208:211], v[28:31]
	v_mfma_f32_16x16x32_bf16 v[24:27], v[164:167], v[208:211], v[24:27]
	v_mfma_f32_16x16x32_bf16 v[12:15], v[156:159], v[216:219], v[12:15]
	v_mfma_f32_16x16x32_bf16 v[8:11], v[164:167], v[216:219], v[8:11]
	v_mfma_f32_16x16x32_bf16 v[52:55], v[168:171], v[188:191], v[52:55]
	v_mfma_f32_16x16x32_bf16 v[48:51], v[176:179], v[188:191], v[48:51]
	v_mfma_f32_16x16x32_bf16 v[36:39], v[168:171], v[196:199], v[36:39]
	v_mfma_f32_16x16x32_bf16 v[32:35], v[176:179], v[196:199], v[32:35]
	v_mfma_f32_16x16x32_bf16 v[20:23], v[168:171], v[204:207], v[20:23]
	v_mfma_f32_16x16x32_bf16 v[16:19], v[176:179], v[204:207], v[16:19]
	v_mfma_f32_16x16x32_bf16 v[4:7], v[168:171], v[212:215], v[4:7]
	v_mfma_f32_16x16x32_bf16 v[0:3], v[176:179], v[212:215], v[0:3]
	v_mfma_f32_16x16x32_bf16 v[52:55], v[172:175], v[192:195], v[52:55]
	v_mfma_f32_16x16x32_bf16 v[48:51], v[184:187], v[192:195], v[48:51]
	v_mfma_f32_16x16x32_bf16 v[36:39], v[172:175], v[200:203], v[36:39]
	v_mfma_f32_16x16x32_bf16 v[32:35], v[184:187], v[200:203], v[32:35]
	v_mfma_f32_16x16x32_bf16 v[20:23], v[172:175], v[208:211], v[20:23]
	v_mfma_f32_16x16x32_bf16 v[16:19], v[184:187], v[208:211], v[16:19]
	v_mfma_f32_16x16x32_bf16 v[4:7], v[172:175], v[216:219], v[4:7]
	v_mfma_f32_16x16x32_bf16 v[0:3], v[184:187], v[216:219], v[0:3]
	s_setprio 0
	s_barrier
	s_add_i32 s51, s51, 2
	s_add_u32 s22, s22, 0x100
	s_addc_u32 s23, s23, 0
	s_add_u32 s49, s49, 0x100
	s_addc_u32 s50, s50, 0
	s_cmp_gt_u32 s51, 13
	s_cbranch_scc0 .LBB0_259
	s_and_b64 vcc, exec, s[10:11]
	s_cbranch_vccz .LBB0_262
	s_barrier

.LBB0_338:
	ds_read_b128 v[150:153], v147
	ds_read_b128 v[154:157], v147 offset:1024
	ds_read_b128 v[158:161], v147 offset:2048
	ds_read_b128 v[162:165], v147 offset:3072
	ds_read_b128 v[166:169], v148
	ds_read_b128 v[170:173], v148 offset:1024
	ds_read_b128 v[174:177], v148 offset:2048
	ds_read_b128 v[178:181], v148 offset:3072
	s_add_u32 s26, s24, 0xfff50080
	s_addc_u32 s27, s25, -1
	s_cmp_eq_u32 s57, 40
	s_cselect_b32 s29, s5, s27
	s_cselect_b32 s28, s4, s26
	s_cselect_b32 s27, s23, s56
	s_cselect_b32 s26, s22, s55
	s_add_i32 m0, s37, 0xc000
	ds_read_b128 v[184:187], v149
	ds_read_b128 v[188:191], v149 offset:1024
	ds_read_b128 v[192:195], v149 offset:2048
	ds_read_b128 v[196:199], v149 offset:3072
	ds_read_b128 v[200:203], v149 offset:4096
	ds_read_b128 v[204:207], v149 offset:5120
	ds_read_b128 v[208:211], v149 offset:6144
	ds_read_b128 v[212:215], v149 offset:7168
	global_load_lds_dwordx4 v136, s[24:25]
	s_add_i32 m0, s37, 0xe000
	s_nop 0
	global_load_lds_dwordx4 v138, s[24:25]
	s_waitcnt vmcnt(8) lgkmcnt(0)
	s_barrier
	s_setprio 1
	v_mfma_f32_16x16x32_bf16 v[124:127], v[150:153], v[184:187], v[124:127]
	v_mfma_f32_16x16x32_bf16 v[120:123], v[158:161], v[184:187], v[120:123]
	v_mfma_f32_16x16x32_bf16 v[116:119], v[150:153], v[192:195], v[116:119]
	v_mfma_f32_16x16x32_bf16 v[112:115], v[158:161], v[192:195], v[112:115]
	v_mfma_f32_16x16x32_bf16 v[100:103], v[150:153], v[200:203], v[100:103]
	v_mfma_f32_16x16x32_bf16 v[96:99], v[158:161], v[200:203], v[96:99]
	v_mfma_f32_16x16x32_bf16 v[84:87], v[150:153], v[208:211], v[84:87]
	v_mfma_f32_16x16x32_bf16 v[80:83], v[158:161], v[208:211], v[80:83]
	v_mfma_f32_16x16x32_bf16 v[124:127], v[154:157], v[188:191], v[124:127]
	v_mfma_f32_16x16x32_bf16 v[120:123], v[162:165], v[188:191], v[120:123]
	v_mfma_f32_16x16x32_bf16 v[116:119], v[154:157], v[196:199], v[116:119]
	v_mfma_f32_16x16x32_bf16 v[112:115], v[162:165], v[196:199], v[112:115]
	v_mfma_f32_16x16x32_bf16 v[100:103], v[154:157], v[204:207], v[100:103]
	v_mfma_f32_16x16x32_bf16 v[96:99], v[162:165], v[204:207], v[96:99]
	v_mfma_f32_16x16x32_bf16 v[84:87], v[154:157], v[212:215], v[84:87]
	v_mfma_f32_16x16x32_bf16 v[80:83], v[162:165], v[212:215], v[80:83]
	v_mfma_f32_16x16x32_bf16 v[108:111], v[166:169], v[184:187], v[108:111]
	v_mfma_f32_16x16x32_bf16 v[104:107], v[174:177], v[184:187], v[104:107]
	v_mfma_f32_16x16x32_bf16 v[92:95], v[166:169], v[192:195], v[92:95]
	v_mfma_f32_16x16x32_bf16 v[88:91], v[174:177], v[192:195], v[88:91]
	v_mfma_f32_16x16x32_bf16 v[76:79], v[166:169], v[200:203], v[76:79]
	v_mfma_f32_16x16x32_bf16 v[72:75], v[174:177], v[200:203], v[72:75]
	v_mfma_f32_16x16x32_bf16 v[68:71], v[166:169], v[208:211], v[68:71]
	v_mfma_f32_16x16x32_bf16 v[64:67], v[174:177], v[208:211], v[64:67]
	v_mfma_f32_16x16x32_bf16 v[108:111], v[170:173], v[188:191], v[108:111]
	v_mfma_f32_16x16x32_bf16 v[104:107], v[178:181], v[188:191], v[104:107]
	v_mfma_f32_16x16x32_bf16 v[92:95], v[170:173], v[196:199], v[92:95]
	v_mfma_f32_16x16x32_bf16 v[88:91], v[178:181], v[196:199], v[88:91]
	v_mfma_f32_16x16x32_bf16 v[76:79], v[170:173], v[204:207], v[76:79]
	v_mfma_f32_16x16x32_bf16 v[72:75], v[178:181], v[204:207], v[72:75]
	v_mfma_f32_16x16x32_bf16 v[68:71], v[170:173], v[212:215], v[68:71]
	v_mfma_f32_16x16x32_bf16 v[64:67], v[178:181], v[212:215], v[64:67]
	s_setprio 0
	s_barrier
	s_add_i32 s58, s45, s36
	v_lshl_add_u64 v[216:217], s[26:27], 0, v[130:131]
	s_mov_b32 m0, s58
	ds_read_b128 v[184:187], v149 offset:16384
	ds_read_b128 v[188:191], v149 offset:17408
	ds_read_b128 v[192:195], v149 offset:18432
	ds_read_b128 v[196:199], v149 offset:19456
	ds_read_b128 v[200:203], v149 offset:20480
	ds_read_b128 v[204:207], v149 offset:21504
	ds_read_b128 v[208:211], v149 offset:22528
	ds_read_b128 v[212:215], v149 offset:23552
	global_load_lds_dwordx4 v[216:217], off
	s_add_i32 m0, s58, 0x2000
	s_add_u32 s58, s26, 0xb0000
	v_lshl_add_u64 v[218:219], s[26:27], 0, v[134:135]
	s_addc_u32 s59, s27, 0
	s_add_i32 s60, s46, s36
	global_load_lds_dwordx4 v[218:219], off
	s_mov_b32 m0, s60
	v_lshl_add_u64 v[222:223], s[28:29], 0, v[132:133]
	global_load_lds_dwordx4 v130, s[58:59]
	s_add_i32 m0, s60, 0x2000
	s_nop 0
	global_load_lds_dwordx4 v134, s[58:59]
	v_lshl_add_u64 v[220:221], s[28:29], 0, v[128:129]
	s_mov_b32 m0, s37
	s_nop 0
	global_load_lds_dwordx4 v[220:221], off
	s_mov_b32 m0, s38
	s_nop 0
	global_load_lds_dwordx4 v[222:223], off
	s_waitcnt vmcnt(8) lgkmcnt(0)
	s_barrier
	s_setprio 1
	v_mfma_f32_16x16x32_bf16 v[60:63], v[150:153], v[184:187], v[60:63]
	v_mfma_f32_16x16x32_bf16 v[56:59], v[158:161], v[184:187], v[56:59]
	v_mfma_f32_16x16x32_bf16 v[52:55], v[150:153], v[192:195], v[52:55]
	v_mfma_f32_16x16x32_bf16 v[48:51], v[158:161], v[192:195], v[48:51]
	v_mfma_f32_16x16x32_bf16 v[36:39], v[150:153], v[200:203], v[36:39]
	v_mfma_f32_16x16x32_bf16 v[32:35], v[158:161], v[200:203], v[32:35]
	v_mfma_f32_16x16x32_bf16 v[20:23], v[150:153], v[208:211], v[20:23]
	v_mfma_f32_16x16x32_bf16 v[16:19], v[158:161], v[208:211], v[16:19]
	v_mfma_f32_16x16x32_bf16 v[60:63], v[154:157], v[188:191], v[60:63]
	v_mfma_f32_16x16x32_bf16 v[56:59], v[162:165], v[188:191], v[56:59]
	v_mfma_f32_16x16x32_bf16 v[52:55], v[154:157], v[196:199], v[52:55]
	v_mfma_f32_16x16x32_bf16 v[48:51], v[162:165], v[196:199], v[48:51]
	v_mfma_f32_16x16x32_bf16 v[36:39], v[154:157], v[204:207], v[36:39]
	v_mfma_f32_16x16x32_bf16 v[32:35], v[162:165], v[204:207], v[32:35]
	v_mfma_f32_16x16x32_bf16 v[20:23], v[154:157], v[212:215], v[20:23]
	v_mfma_f32_16x16x32_bf16 v[16:19], v[162:165], v[212:215], v[16:19]
	v_mfma_f32_16x16x32_bf16 v[44:47], v[166:169], v[184:187], v[44:47]
	v_mfma_f32_16x16x32_bf16 v[40:43], v[174:177], v[184:187], v[40:43]
	v_mfma_f32_16x16x32_bf16 v[28:31], v[166:169], v[192:195], v[28:31]
	v_mfma_f32_16x16x32_bf16 v[24:27], v[174:177], v[192:195], v[24:27]
	v_mfma_f32_16x16x32_bf16 v[12:15], v[166:169], v[200:203], v[12:15]
	v_mfma_f32_16x16x32_bf16 v[8:11], v[174:177], v[200:203], v[8:11]
	v_mfma_f32_16x16x32_bf16 v[4:7], v[166:169], v[208:211], v[4:7]
	v_mfma_f32_16x16x32_bf16 v[0:3], v[174:177], v[208:211], v[0:3]
	v_mfma_f32_16x16x32_bf16 v[44:47], v[170:173], v[188:191], v[44:47]
	v_mfma_f32_16x16x32_bf16 v[40:43], v[178:181], v[188:191], v[40:43]
	v_mfma_f32_16x16x32_bf16 v[28:31], v[170:173], v[196:199], v[28:31]
	v_mfma_f32_16x16x32_bf16 v[24:27], v[178:181], v[196:199], v[24:27]
	v_mfma_f32_16x16x32_bf16 v[12:15], v[170:173], v[204:207], v[12:15]
	v_mfma_f32_16x16x32_bf16 v[8:11], v[178:181], v[204:207], v[8:11]
	v_mfma_f32_16x16x32_bf16 v[4:7], v[170:173], v[212:215], v[4:7]
	v_mfma_f32_16x16x32_bf16 v[0:3], v[178:181], v[212:215], v[0:3]
	s_setprio 0
	s_barrier
	s_add_i32 s58, 0, 0x18000
	s_add_i32 s59, 0, 0x1c000
	v_add_u32_e32 v162, s58, v145
	v_add_u32_e32 v178, s59, v145
	ds_read_b128 v[150:153], v162
	ds_read_b128 v[154:157], v162 offset:1024
	ds_read_b128 v[158:161], v162 offset:2048
	ds_read_b128 v[162:165], v162 offset:3072
	ds_read_b128 v[166:169], v178
	ds_read_b128 v[170:173], v178 offset:1024
	ds_read_b128 v[174:177], v178 offset:2048
	ds_read_b128 v[178:181], v178 offset:3072
	s_add_u32 s28, s28, 0xb0000
	s_addc_u32 s29, s29, 0
	s_mov_b32 m0, s39
	ds_read_b128 v[184:187], v149 offset:32768
	ds_read_b128 v[188:191], v149 offset:33792
	ds_read_b128 v[192:195], v149 offset:34816
	ds_read_b128 v[196:199], v149 offset:35840
	ds_read_b128 v[200:203], v149 offset:36864
	ds_read_b128 v[204:207], v149 offset:37888
	ds_read_b128 v[208:211], v149 offset:38912
	ds_read_b128 v[212:215], v149 offset:39936
	global_load_lds_dwordx4 v128, s[28:29]
	s_mov_b32 m0, s40
	s_nop 0
	global_load_lds_dwordx4 v132, s[28:29]
	s_waitcnt vmcnt(8) lgkmcnt(0)
	s_barrier
	s_setprio 1
	v_mfma_f32_16x16x32_bf16 v[124:127], v[150:153], v[184:187], v[124:127]
	v_mfma_f32_16x16x32_bf16 v[120:123], v[158:161], v[184:187], v[120:123]
	v_mfma_f32_16x16x32_bf16 v[116:119], v[150:153], v[192:195], v[116:119]
	v_mfma_f32_16x16x32_bf16 v[112:115], v[158:161], v[192:195], v[112:115]
	v_mfma_f32_16x16x32_bf16 v[100:103], v[150:153], v[200:203], v[100:103]
	v_mfma_f32_16x16x32_bf16 v[96:99], v[158:161], v[200:203], v[96:99]
	v_mfma_f32_16x16x32_bf16 v[84:87], v[150:153], v[208:211], v[84:87]
	v_mfma_f32_16x16x32_bf16 v[80:83], v[158:161], v[208:211], v[80:83]
	v_mfma_f32_16x16x32_bf16 v[124:127], v[154:157], v[188:191], v[124:127]
	v_mfma_f32_16x16x32_bf16 v[120:123], v[162:165], v[188:191], v[120:123]
	v_mfma_f32_16x16x32_bf16 v[116:119], v[154:157], v[196:199], v[116:119]
	v_mfma_f32_16x16x32_bf16 v[112:115], v[162:165], v[196:199], v[112:115]
	v_mfma_f32_16x16x32_bf16 v[100:103], v[154:157], v[204:207], v[100:103]
	v_mfma_f32_16x16x32_bf16 v[96:99], v[162:165], v[204:207], v[96:99]
	v_mfma_f32_16x16x32_bf16 v[84:87], v[154:157], v[212:215], v[84:87]
	v_mfma_f32_16x16x32_bf16 v[80:83], v[162:165], v[212:215], v[80:83]
	v_mfma_f32_16x16x32_bf16 v[108:111], v[166:169], v[184:187], v[108:111]
	v_mfma_f32_16x16x32_bf16 v[104:107], v[174:177], v[184:187], v[104:107]
	v_mfma_f32_16x16x32_bf16 v[92:95], v[166:169], v[192:195], v[92:95]
	v_mfma_f32_16x16x32_bf16 v[88:91], v[174:177], v[192:195], v[88:91]
	v_mfma_f32_16x16x32_bf16 v[76:79], v[166:169], v[200:203], v[76:79]
	v_mfma_f32_16x16x32_bf16 v[72:75], v[174:177], v[200:203], v[72:75]
	v_mfma_f32_16x16x32_bf16 v[68:71], v[166:169], v[208:211], v[68:71]
	v_mfma_f32_16x16x32_bf16 v[64:67], v[174:177], v[208:211], v[64:67]
	v_mfma_f32_16x16x32_bf16 v[108:111], v[170:173], v[188:191], v[108:111]
	v_mfma_f32_16x16x32_bf16 v[104:107], v[178:181], v[188:191], v[104:107]
	v_mfma_f32_16x16x32_bf16 v[92:95], v[170:173], v[196:199], v[92:95]
	v_mfma_f32_16x16x32_bf16 v[88:91], v[178:181], v[196:199], v[88:91]
	v_mfma_f32_16x16x32_bf16 v[76:79], v[170:173], v[204:207], v[76:79]
	v_mfma_f32_16x16x32_bf16 v[72:75], v[178:181], v[204:207], v[72:75]
	v_mfma_f32_16x16x32_bf16 v[68:71], v[170:173], v[212:215], v[68:71]
	v_mfma_f32_16x16x32_bf16 v[64:67], v[178:181], v[212:215], v[64:67]
	s_setprio 0
	s_barrier
	s_add_i32 s28, s58, s36
	v_lshl_add_u64 v[216:217], v[216:217], 0, s[10:11]
	s_mov_b32 m0, s28
	ds_read_b128 v[184:187], v149 offset:49152
	ds_read_b128 v[188:191], v149 offset:50176
	ds_read_b128 v[192:195], v149 offset:51200
	ds_read_b128 v[196:199], v149 offset:52224
	ds_read_b128 v[200:203], v149 offset:53248
	ds_read_b128 v[204:207], v149 offset:54272
	ds_read_b128 v[208:211], v149 offset:55296
	ds_read_b128 v[212:215], v149 offset:56320
	global_load_lds_dwordx4 v[216:217], off
	s_add_i32 m0, s28, 0x2000
	s_add_u32 s26, s26, 0xb0080
	v_lshl_add_u64 v[216:217], v[218:219], 0, s[10:11]
	s_addc_u32 s27, s27, 0
	s_add_i32 s28, s59, s36
	global_load_lds_dwordx4 v[216:217], off
	s_mov_b32 m0, s28
	s_nop 0
	global_load_lds_dwordx4 v130, s[26:27]
	s_add_i32 m0, s28, 0x2000
	s_nop 0
	global_load_lds_dwordx4 v134, s[26:27]
	v_lshl_add_u64 v[216:217], v[220:221], 0, s[10:11]
	s_mov_b32 m0, s43
	s_nop 0
	global_load_lds_dwordx4 v[216:217], off
	v_lshl_add_u64 v[216:217], v[222:223], 0, s[10:11]
	s_mov_b32 m0, s44
	s_nop 0
	global_load_lds_dwordx4 v[216:217], off
	s_waitcnt vmcnt(8) lgkmcnt(0)
	s_barrier
	s_setprio 1
	v_mfma_f32_16x16x32_bf16 v[60:63], v[150:153], v[184:187], v[60:63]
	v_mfma_f32_16x16x32_bf16 v[56:59], v[158:161], v[184:187], v[56:59]
	v_mfma_f32_16x16x32_bf16 v[52:55], v[150:153], v[192:195], v[52:55]
	v_mfma_f32_16x16x32_bf16 v[48:51], v[158:161], v[192:195], v[48:51]
	v_mfma_f32_16x16x32_bf16 v[36:39], v[150:153], v[200:203], v[36:39]
	v_mfma_f32_16x16x32_bf16 v[32:35], v[158:161], v[200:203], v[32:35]
	v_mfma_f32_16x16x32_bf16 v[20:23], v[150:153], v[208:211], v[20:23]
	v_mfma_f32_16x16x32_bf16 v[16:19], v[158:161], v[208:211], v[16:19]
	v_mfma_f32_16x16x32_bf16 v[60:63], v[154:157], v[188:191], v[60:63]
	v_mfma_f32_16x16x32_bf16 v[56:59], v[162:165], v[188:191], v[56:59]
	v_mfma_f32_16x16x32_bf16 v[52:55], v[154:157], v[196:199], v[52:55]
	v_mfma_f32_16x16x32_bf16 v[48:51], v[162:165], v[196:199], v[48:51]
	v_mfma_f32_16x16x32_bf16 v[36:39], v[154:157], v[204:207], v[36:39]
	v_mfma_f32_16x16x32_bf16 v[32:35], v[162:165], v[204:207], v[32:35]
	v_mfma_f32_16x16x32_bf16 v[20:23], v[154:157], v[212:215], v[20:23]
	v_mfma_f32_16x16x32_bf16 v[16:19], v[162:165], v[212:215], v[16:19]
	v_mfma_f32_16x16x32_bf16 v[44:47], v[166:169], v[184:187], v[44:47]
	v_mfma_f32_16x16x32_bf16 v[40:43], v[174:177], v[184:187], v[40:43]
	v_mfma_f32_16x16x32_bf16 v[28:31], v[166:169], v[192:195], v[28:31]
	v_mfma_f32_16x16x32_bf16 v[24:27], v[174:177], v[192:195], v[24:27]
	v_mfma_f32_16x16x32_bf16 v[12:15], v[166:169], v[200:203], v[12:15]
	v_mfma_f32_16x16x32_bf16 v[8:11], v[174:177], v[200:203], v[8:11]
	v_mfma_f32_16x16x32_bf16 v[4:7], v[166:169], v[208:211], v[4:7]
	v_mfma_f32_16x16x32_bf16 v[0:3], v[174:177], v[208:211], v[0:3]
	v_mfma_f32_16x16x32_bf16 v[44:47], v[170:173], v[188:191], v[44:47]
	v_mfma_f32_16x16x32_bf16 v[40:43], v[178:181], v[188:191], v[40:43]
	v_mfma_f32_16x16x32_bf16 v[28:31], v[170:173], v[196:199], v[28:31]
	v_mfma_f32_16x16x32_bf16 v[24:27], v[178:181], v[196:199], v[24:27]
	v_mfma_f32_16x16x32_bf16 v[12:15], v[170:173], v[204:207], v[12:15]
	v_mfma_f32_16x16x32_bf16 v[8:11], v[178:181], v[204:207], v[8:11]
	v_mfma_f32_16x16x32_bf16 v[4:7], v[170:173], v[212:215], v[4:7]
	v_mfma_f32_16x16x32_bf16 v[0:3], v[178:181], v[212:215], v[0:3]
	s_setprio 0
	s_barrier
	s_add_i32 s57, s57, 2
	s_add_u32 s24, s24, 0x100
	s_addc_u32 s25, s25, 0
	s_add_u32 s55, s55, 0x100
	s_addc_u32 s56, s56, 0
	s_cmp_gt_u32 s57, 41
	s_cbranch_scc0 .LBB0_338
	s_and_b64 vcc, exec, s[12:13]
	s_cbranch_vccz .LBB0_341
	s_barrier

.LBB0_475:
	ds_read_b128 v[150:153], v158
	ds_read_b128 v[162:165], v158 offset:1024
	ds_read_b128 v[166:169], v158 offset:2048
	ds_read_b128 v[170:173], v158 offset:3072
	ds_read_b128 v[174:177], v159
	ds_read_b128 v[178:181], v159 offset:1024
	ds_read_b128 v[184:187], v159 offset:2048
	ds_read_b128 v[188:191], v159 offset:3072
	s_add_u32 s48, s46, 0xfffc0080
	s_addc_u32 s49, s47, -1
	s_cmp_eq_u32 s77, 12
	s_cselect_b32 s51, s1, s49
	s_cselect_b32 s50, s39, s48
	s_cselect_b32 s49, s37, s76
	s_cselect_b32 s48, s45, s75
	s_add_i32 m0, s57, 0xc000
	ds_read_b128 v[192:195], v160
	ds_read_b128 v[196:199], v160 offset:1024
	ds_read_b128 v[200:203], v160 offset:2048
	ds_read_b128 v[204:207], v160 offset:3072
	ds_read_b128 v[208:211], v160 offset:4096
	ds_read_b128 v[212:215], v160 offset:5120
	ds_read_b128 v[216:219], v160 offset:6144
	ds_read_b128 v[220:223], v160 offset:7168
	global_load_lds_dwordx4 v142, s[46:47]
	s_add_i32 m0, s57, 0xe000
	s_nop 0
	global_load_lds_dwordx4 v144, s[46:47]
	s_waitcnt vmcnt(8) lgkmcnt(0)
	s_barrier
	s_setprio 1
	v_mfma_f32_16x16x32_bf16 v[64:67], v[150:153], v[192:195], v[64:67]
	v_mfma_f32_16x16x32_bf16 v[28:31], v[166:169], v[192:195], v[28:31]
	v_mfma_f32_16x16x32_bf16 v[60:63], v[150:153], v[200:203], v[60:63]
	v_mfma_f32_16x16x32_bf16 v[24:27], v[166:169], v[200:203], v[24:27]
	v_mfma_f32_16x16x32_bf16 v[56:59], v[150:153], v[208:211], v[56:59]
	v_mfma_f32_16x16x32_bf16 v[20:23], v[166:169], v[208:211], v[20:23]
	v_mfma_f32_16x16x32_bf16 v[52:55], v[150:153], v[216:219], v[52:55]
	v_mfma_f32_16x16x32_bf16 v[16:19], v[166:169], v[216:219], v[16:19]
	v_mfma_f32_16x16x32_bf16 v[64:67], v[162:165], v[196:199], v[64:67]
	v_mfma_f32_16x16x32_bf16 v[28:31], v[170:173], v[196:199], v[28:31]
	v_mfma_f32_16x16x32_bf16 v[60:63], v[162:165], v[204:207], v[60:63]
	v_mfma_f32_16x16x32_bf16 v[24:27], v[170:173], v[204:207], v[24:27]
	v_mfma_f32_16x16x32_bf16 v[56:59], v[162:165], v[212:215], v[56:59]
	v_mfma_f32_16x16x32_bf16 v[20:23], v[170:173], v[212:215], v[20:23]
	v_mfma_f32_16x16x32_bf16 v[52:55], v[162:165], v[220:223], v[52:55]
	v_mfma_f32_16x16x32_bf16 v[16:19], v[170:173], v[220:223], v[16:19]
	v_mfma_f32_16x16x32_bf16 v[124:127], v[174:177], v[192:195], v[124:127]
	v_mfma_f32_16x16x32_bf16 v[120:123], v[184:187], v[192:195], v[120:123]
	v_mfma_f32_16x16x32_bf16 v[116:119], v[174:177], v[200:203], v[116:119]
	v_mfma_f32_16x16x32_bf16 v[112:115], v[184:187], v[200:203], v[112:115]
	v_mfma_f32_16x16x32_bf16 v[108:111], v[174:177], v[208:211], v[108:111]
	v_mfma_f32_16x16x32_bf16 v[104:107], v[184:187], v[208:211], v[104:107]
	v_mfma_f32_16x16x32_bf16 v[100:103], v[174:177], v[216:219], v[100:103]
	v_mfma_f32_16x16x32_bf16 v[96:99], v[184:187], v[216:219], v[96:99]
	v_mfma_f32_16x16x32_bf16 v[124:127], v[178:181], v[196:199], v[124:127]
	v_mfma_f32_16x16x32_bf16 v[120:123], v[188:191], v[196:199], v[120:123]
	v_mfma_f32_16x16x32_bf16 v[116:119], v[178:181], v[204:207], v[116:119]
	v_mfma_f32_16x16x32_bf16 v[112:115], v[188:191], v[204:207], v[112:115]
	v_mfma_f32_16x16x32_bf16 v[108:111], v[178:181], v[212:215], v[108:111]
	v_mfma_f32_16x16x32_bf16 v[104:107], v[188:191], v[212:215], v[104:107]
	v_mfma_f32_16x16x32_bf16 v[100:103], v[178:181], v[220:223], v[100:103]
	v_mfma_f32_16x16x32_bf16 v[96:99], v[188:191], v[220:223], v[96:99]
	s_setprio 0
	s_barrier
	s_add_i32 s78, s66, s56
	v_lshl_add_u64 v[224:225], s[48:49], 0, v[130:131]
	s_mov_b32 m0, s78
	ds_read_b128 v[192:195], v160 offset:16384
	ds_read_b128 v[196:199], v160 offset:17408
	ds_read_b128 v[200:203], v160 offset:18432
	ds_read_b128 v[204:207], v160 offset:19456
	ds_read_b128 v[208:211], v160 offset:20480
	ds_read_b128 v[212:215], v160 offset:21504
	ds_read_b128 v[216:219], v160 offset:22528
	ds_read_b128 v[220:223], v160 offset:23552
	global_load_lds_dwordx4 v[224:225], off
	s_add_i32 m0, s78, 0x2000
	s_add_u32 s78, s48, 0x40000
	v_lshl_add_u64 v[226:227], s[48:49], 0, v[134:135]
	s_addc_u32 s79, s49, 0
	s_add_i32 s80, s67, s56
	global_load_lds_dwordx4 v[226:227], off
	s_mov_b32 m0, s80
	v_lshl_add_u64 v[230:231], s[50:51], 0, v[132:133]
	global_load_lds_dwordx4 v130, s[78:79]
	s_add_i32 m0, s80, 0x2000
	s_nop 0
	global_load_lds_dwordx4 v134, s[78:79]
	v_lshl_add_u64 v[228:229], s[50:51], 0, v[128:129]
	s_mov_b32 m0, s57
	s_nop 0
	global_load_lds_dwordx4 v[228:229], off
	s_mov_b32 m0, s58
	s_nop 0
	global_load_lds_dwordx4 v[230:231], off
	s_waitcnt vmcnt(8) lgkmcnt(0)
	s_barrier
	s_setprio 1
	v_mfma_f32_16x16x32_bf16 v[44:47], v[150:153], v[192:195], v[44:47]
	v_mfma_f32_16x16x32_bf16 v[12:15], v[166:169], v[192:195], v[12:15]
	v_mfma_f32_16x16x32_bf16 v[40:43], v[150:153], v[200:203], v[40:43]
	v_mfma_f32_16x16x32_bf16 v[8:11], v[166:169], v[200:203], v[8:11]
	v_mfma_f32_16x16x32_bf16 v[36:39], v[150:153], v[208:211], v[36:39]
	v_mfma_f32_16x16x32_bf16 v[4:7], v[166:169], v[208:211], v[4:7]
	v_mfma_f32_16x16x32_bf16 v[32:35], v[150:153], v[216:219], v[32:35]
	v_mfma_f32_16x16x32_bf16 v[0:3], v[166:169], v[216:219], v[0:3]
	v_mfma_f32_16x16x32_bf16 v[44:47], v[162:165], v[196:199], v[44:47]
	v_mfma_f32_16x16x32_bf16 v[12:15], v[170:173], v[196:199], v[12:15]
	v_mfma_f32_16x16x32_bf16 v[40:43], v[162:165], v[204:207], v[40:43]
	v_mfma_f32_16x16x32_bf16 v[8:11], v[170:173], v[204:207], v[8:11]
	v_mfma_f32_16x16x32_bf16 v[36:39], v[162:165], v[212:215], v[36:39]
	v_mfma_f32_16x16x32_bf16 v[4:7], v[170:173], v[212:215], v[4:7]
	v_mfma_f32_16x16x32_bf16 v[32:35], v[162:165], v[220:223], v[32:35]
	v_mfma_f32_16x16x32_bf16 v[0:3], v[170:173], v[220:223], v[0:3]
	v_mfma_f32_16x16x32_bf16 v[92:95], v[174:177], v[192:195], v[92:95]
	v_mfma_f32_16x16x32_bf16 v[88:91], v[184:187], v[192:195], v[88:91]
	v_mfma_f32_16x16x32_bf16 v[84:87], v[174:177], v[200:203], v[84:87]
	v_mfma_f32_16x16x32_bf16 v[80:83], v[184:187], v[200:203], v[80:83]
	v_mfma_f32_16x16x32_bf16 v[76:79], v[174:177], v[208:211], v[76:79]
	v_mfma_f32_16x16x32_bf16 v[72:75], v[184:187], v[208:211], v[72:75]
	v_mfma_f32_16x16x32_bf16 v[68:71], v[174:177], v[216:219], v[68:71]
	v_mfma_f32_16x16x32_bf16 v[48:51], v[184:187], v[216:219], v[48:51]
	v_mfma_f32_16x16x32_bf16 v[92:95], v[178:181], v[196:199], v[92:95]
	v_mfma_f32_16x16x32_bf16 v[88:91], v[188:191], v[196:199], v[88:91]
	v_mfma_f32_16x16x32_bf16 v[84:87], v[178:181], v[204:207], v[84:87]
	v_mfma_f32_16x16x32_bf16 v[80:83], v[188:191], v[204:207], v[80:83]
	v_mfma_f32_16x16x32_bf16 v[76:79], v[178:181], v[212:215], v[76:79]
	v_mfma_f32_16x16x32_bf16 v[72:75], v[188:191], v[212:215], v[72:75]
	v_mfma_f32_16x16x32_bf16 v[68:71], v[178:181], v[220:223], v[68:71]
	v_mfma_f32_16x16x32_bf16 v[48:51], v[188:191], v[220:223], v[48:51]
	s_setprio 0
	s_barrier
	s_add_i32 s78, 0, 0x18000
	v_add_u32_e32 v136, s78, v156
	s_add_i32 s79, 0, 0x1c000
	ds_read_b128 v[150:153], v136
	ds_read_b128 v[162:165], v136 offset:1024
	ds_read_b128 v[166:169], v136 offset:2048
	ds_read_b128 v[170:173], v136 offset:3072
	v_add_u32_e32 v136, s79, v156
	ds_read_b128 v[174:177], v136
	ds_read_b128 v[178:181], v136 offset:1024
	ds_read_b128 v[184:187], v136 offset:2048
	ds_read_b128 v[188:191], v136 offset:3072
	s_add_u32 s50, s50, 0x40000
	s_addc_u32 s51, s51, 0
	s_mov_b32 m0, s59
	ds_read_b128 v[192:195], v160 offset:32768
	ds_read_b128 v[196:199], v160 offset:33792
	ds_read_b128 v[200:203], v160 offset:34816
	ds_read_b128 v[204:207], v160 offset:35840
	ds_read_b128 v[208:211], v160 offset:36864
	ds_read_b128 v[212:215], v160 offset:37888
	ds_read_b128 v[216:219], v160 offset:38912
	ds_read_b128 v[220:223], v160 offset:39936
	global_load_lds_dwordx4 v128, s[50:51]
	s_mov_b32 m0, s60
	s_nop 0
	global_load_lds_dwordx4 v132, s[50:51]
	s_waitcnt vmcnt(8) lgkmcnt(0)
	s_barrier
	s_setprio 1
	v_mfma_f32_16x16x32_bf16 v[64:67], v[150:153], v[192:195], v[64:67]
	v_mfma_f32_16x16x32_bf16 v[28:31], v[166:169], v[192:195], v[28:31]
	v_mfma_f32_16x16x32_bf16 v[60:63], v[150:153], v[200:203], v[60:63]
	v_mfma_f32_16x16x32_bf16 v[24:27], v[166:169], v[200:203], v[24:27]
	v_mfma_f32_16x16x32_bf16 v[56:59], v[150:153], v[208:211], v[56:59]
	v_mfma_f32_16x16x32_bf16 v[20:23], v[166:169], v[208:211], v[20:23]
	v_mfma_f32_16x16x32_bf16 v[52:55], v[150:153], v[216:219], v[52:55]
	v_mfma_f32_16x16x32_bf16 v[16:19], v[166:169], v[216:219], v[16:19]
	v_mfma_f32_16x16x32_bf16 v[64:67], v[162:165], v[196:199], v[64:67]
	v_mfma_f32_16x16x32_bf16 v[28:31], v[170:173], v[196:199], v[28:31]
	v_mfma_f32_16x16x32_bf16 v[60:63], v[162:165], v[204:207], v[60:63]
	v_mfma_f32_16x16x32_bf16 v[24:27], v[170:173], v[204:207], v[24:27]
	v_mfma_f32_16x16x32_bf16 v[56:59], v[162:165], v[212:215], v[56:59]
	v_mfma_f32_16x16x32_bf16 v[20:23], v[170:173], v[212:215], v[20:23]
	v_mfma_f32_16x16x32_bf16 v[52:55], v[162:165], v[220:223], v[52:55]
	v_mfma_f32_16x16x32_bf16 v[16:19], v[170:173], v[220:223], v[16:19]
	v_mfma_f32_16x16x32_bf16 v[124:127], v[174:177], v[192:195], v[124:127]
	v_mfma_f32_16x16x32_bf16 v[120:123], v[184:187], v[192:195], v[120:123]
	v_mfma_f32_16x16x32_bf16 v[116:119], v[174:177], v[200:203], v[116:119]
	v_mfma_f32_16x16x32_bf16 v[112:115], v[184:187], v[200:203], v[112:115]
	v_mfma_f32_16x16x32_bf16 v[108:111], v[174:177], v[208:211], v[108:111]
	v_mfma_f32_16x16x32_bf16 v[104:107], v[184:187], v[208:211], v[104:107]
	v_mfma_f32_16x16x32_bf16 v[100:103], v[174:177], v[216:219], v[100:103]
	v_mfma_f32_16x16x32_bf16 v[96:99], v[184:187], v[216:219], v[96:99]
	v_mfma_f32_16x16x32_bf16 v[124:127], v[178:181], v[196:199], v[124:127]
	v_mfma_f32_16x16x32_bf16 v[120:123], v[188:191], v[196:199], v[120:123]
	v_mfma_f32_16x16x32_bf16 v[116:119], v[178:181], v[204:207], v[116:119]
	v_mfma_f32_16x16x32_bf16 v[112:115], v[188:191], v[204:207], v[112:115]
	v_mfma_f32_16x16x32_bf16 v[108:111], v[178:181], v[212:215], v[108:111]
	v_mfma_f32_16x16x32_bf16 v[104:107], v[188:191], v[212:215], v[104:107]
	v_mfma_f32_16x16x32_bf16 v[100:103], v[178:181], v[220:223], v[100:103]
	v_mfma_f32_16x16x32_bf16 v[96:99], v[188:191], v[220:223], v[96:99]
	s_setprio 0
	s_barrier
	s_add_i32 s50, s78, s56
	v_lshl_add_u64 v[224:225], v[224:225], 0, s[28:29]
	s_mov_b32 m0, s50
	ds_read_b128 v[192:195], v160 offset:49152
	ds_read_b128 v[196:199], v160 offset:50176
	ds_read_b128 v[200:203], v160 offset:51200
	ds_read_b128 v[204:207], v160 offset:52224
	ds_read_b128 v[208:211], v160 offset:53248
	ds_read_b128 v[212:215], v160 offset:54272
	ds_read_b128 v[216:219], v160 offset:55296
	ds_read_b128 v[220:223], v160 offset:56320
	global_load_lds_dwordx4 v[224:225], off
	s_add_i32 m0, s50, 0x2000
	s_add_u32 s48, s48, 0x40080
	v_lshl_add_u64 v[224:225], v[226:227], 0, s[28:29]
	s_addc_u32 s49, s49, 0
	s_add_i32 s50, s79, s56
	global_load_lds_dwordx4 v[224:225], off
	s_mov_b32 m0, s50
	s_nop 0
	global_load_lds_dwordx4 v130, s[48:49]
	s_add_i32 m0, s50, 0x2000
	s_nop 0
	global_load_lds_dwordx4 v134, s[48:49]
	v_lshl_add_u64 v[224:225], v[228:229], 0, s[28:29]
	s_mov_b32 m0, s63
	s_nop 0
	global_load_lds_dwordx4 v[224:225], off
	v_lshl_add_u64 v[224:225], v[230:231], 0, s[28:29]
	s_mov_b32 m0, s64
	s_nop 0
	global_load_lds_dwordx4 v[224:225], off
	s_waitcnt vmcnt(8) lgkmcnt(0)
	s_barrier
	s_setprio 1
	v_mfma_f32_16x16x32_bf16 v[44:47], v[150:153], v[192:195], v[44:47]
	v_mfma_f32_16x16x32_bf16 v[12:15], v[166:169], v[192:195], v[12:15]
	v_mfma_f32_16x16x32_bf16 v[40:43], v[150:153], v[200:203], v[40:43]
	v_mfma_f32_16x16x32_bf16 v[8:11], v[166:169], v[200:203], v[8:11]
	v_mfma_f32_16x16x32_bf16 v[36:39], v[150:153], v[208:211], v[36:39]
	v_mfma_f32_16x16x32_bf16 v[4:7], v[166:169], v[208:211], v[4:7]
	v_mfma_f32_16x16x32_bf16 v[32:35], v[150:153], v[216:219], v[32:35]
	v_mfma_f32_16x16x32_bf16 v[0:3], v[166:169], v[216:219], v[0:3]
	v_mfma_f32_16x16x32_bf16 v[44:47], v[162:165], v[196:199], v[44:47]
	v_mfma_f32_16x16x32_bf16 v[12:15], v[170:173], v[196:199], v[12:15]
	v_mfma_f32_16x16x32_bf16 v[40:43], v[162:165], v[204:207], v[40:43]
	v_mfma_f32_16x16x32_bf16 v[8:11], v[170:173], v[204:207], v[8:11]
	v_mfma_f32_16x16x32_bf16 v[36:39], v[162:165], v[212:215], v[36:39]
	v_mfma_f32_16x16x32_bf16 v[4:7], v[170:173], v[212:215], v[4:7]
	v_mfma_f32_16x16x32_bf16 v[32:35], v[162:165], v[220:223], v[32:35]
	v_mfma_f32_16x16x32_bf16 v[0:3], v[170:173], v[220:223], v[0:3]
	v_mfma_f32_16x16x32_bf16 v[92:95], v[174:177], v[192:195], v[92:95]
	v_mfma_f32_16x16x32_bf16 v[88:91], v[184:187], v[192:195], v[88:91]
	v_mfma_f32_16x16x32_bf16 v[84:87], v[174:177], v[200:203], v[84:87]
	v_mfma_f32_16x16x32_bf16 v[80:83], v[184:187], v[200:203], v[80:83]
	v_mfma_f32_16x16x32_bf16 v[76:79], v[174:177], v[208:211], v[76:79]
	v_mfma_f32_16x16x32_bf16 v[72:75], v[184:187], v[208:211], v[72:75]
	v_mfma_f32_16x16x32_bf16 v[68:71], v[174:177], v[216:219], v[68:71]
	v_mfma_f32_16x16x32_bf16 v[48:51], v[184:187], v[216:219], v[48:51]
	v_mfma_f32_16x16x32_bf16 v[92:95], v[178:181], v[196:199], v[92:95]
	v_mfma_f32_16x16x32_bf16 v[88:91], v[188:191], v[196:199], v[88:91]
	v_mfma_f32_16x16x32_bf16 v[84:87], v[178:181], v[204:207], v[84:87]
	v_mfma_f32_16x16x32_bf16 v[80:83], v[188:191], v[204:207], v[80:83]
	v_mfma_f32_16x16x32_bf16 v[76:79], v[178:181], v[212:215], v[76:79]
	v_mfma_f32_16x16x32_bf16 v[72:75], v[188:191], v[212:215], v[72:75]
	v_mfma_f32_16x16x32_bf16 v[68:71], v[178:181], v[220:223], v[68:71]
	v_mfma_f32_16x16x32_bf16 v[48:51], v[188:191], v[220:223], v[48:51]
	s_setprio 0
	s_barrier
	s_add_i32 s77, s77, 2
	s_add_u32 s46, s46, 0x100
	s_addc_u32 s47, s47, 0
	s_add_u32 s75, s75, 0x100
	s_addc_u32 s76, s76, 0
	s_cmp_gt_u32 s77, 13
	s_cbranch_scc0 .LBB0_475
	s_and_b64 vcc, exec, s[30:31]
	s_cbranch_vccnz .LBB0_479
	v_lshl_add_u32 v162, s44, 8, v155
	s_cmp_lg_u32 s0, 22
	s_mov_b64 s[44:45], -1
	s_cbranch_scc1 .LBB0_480

.LBB0_1274:
	ds_read_b128 v[150:153], v147
	ds_read_b128 v[154:157], v147 offset:1024
	ds_read_b128 v[158:161], v147 offset:2048
	ds_read_b128 v[162:165], v147 offset:3072
	ds_read_b128 v[166:169], v148
	ds_read_b128 v[170:173], v148 offset:1024
	ds_read_b128 v[174:177], v148 offset:2048
	ds_read_b128 v[178:181], v148 offset:3072
	s_add_u32 s28, s4, 0xffea0080
	s_addc_u32 s29, s5, -1
	s_cmp_eq_u32 s59, 28
	s_cselect_b32 s31, s25, s29
	s_cselect_b32 s30, s24, s28
	s_cselect_b32 s29, s23, s58
	s_cselect_b32 s28, s56, s57
	s_add_i32 m0, s39, 0xc000
	ds_read_b128 v[184:187], v149
	ds_read_b128 v[188:191], v149 offset:1024
	ds_read_b128 v[192:195], v149 offset:2048
	ds_read_b128 v[196:199], v149 offset:3072
	ds_read_b128 v[200:203], v149 offset:4096
	ds_read_b128 v[204:207], v149 offset:5120
	ds_read_b128 v[208:211], v149 offset:6144
	ds_read_b128 v[212:215], v149 offset:7168
	global_load_lds_dwordx4 v136, s[4:5]
	s_add_i32 m0, s39, 0xe000
	s_nop 0
	global_load_lds_dwordx4 v138, s[4:5]
	s_waitcnt vmcnt(8) lgkmcnt(0)
	s_barrier
	s_setprio 1
	v_mfma_f32_16x16x32_bf16 v[124:127], v[150:153], v[184:187], v[124:127]
	v_mfma_f32_16x16x32_bf16 v[120:123], v[158:161], v[184:187], v[120:123]
	v_mfma_f32_16x16x32_bf16 v[116:119], v[150:153], v[192:195], v[116:119]
	v_mfma_f32_16x16x32_bf16 v[112:115], v[158:161], v[192:195], v[112:115]
	v_mfma_f32_16x16x32_bf16 v[100:103], v[150:153], v[200:203], v[100:103]
	v_mfma_f32_16x16x32_bf16 v[96:99], v[158:161], v[200:203], v[96:99]
	v_mfma_f32_16x16x32_bf16 v[84:87], v[150:153], v[208:211], v[84:87]
	v_mfma_f32_16x16x32_bf16 v[80:83], v[158:161], v[208:211], v[80:83]
	v_mfma_f32_16x16x32_bf16 v[124:127], v[154:157], v[188:191], v[124:127]
	v_mfma_f32_16x16x32_bf16 v[120:123], v[162:165], v[188:191], v[120:123]
	v_mfma_f32_16x16x32_bf16 v[116:119], v[154:157], v[196:199], v[116:119]
	v_mfma_f32_16x16x32_bf16 v[112:115], v[162:165], v[196:199], v[112:115]
	v_mfma_f32_16x16x32_bf16 v[100:103], v[154:157], v[204:207], v[100:103]
	v_mfma_f32_16x16x32_bf16 v[96:99], v[162:165], v[204:207], v[96:99]
	v_mfma_f32_16x16x32_bf16 v[84:87], v[154:157], v[212:215], v[84:87]
	v_mfma_f32_16x16x32_bf16 v[80:83], v[162:165], v[212:215], v[80:83]
	v_mfma_f32_16x16x32_bf16 v[108:111], v[166:169], v[184:187], v[108:111]
	v_mfma_f32_16x16x32_bf16 v[104:107], v[174:177], v[184:187], v[104:107]
	v_mfma_f32_16x16x32_bf16 v[92:95], v[166:169], v[192:195], v[92:95]
	v_mfma_f32_16x16x32_bf16 v[88:91], v[174:177], v[192:195], v[88:91]
	v_mfma_f32_16x16x32_bf16 v[76:79], v[166:169], v[200:203], v[76:79]
	v_mfma_f32_16x16x32_bf16 v[72:75], v[174:177], v[200:203], v[72:75]
	v_mfma_f32_16x16x32_bf16 v[68:71], v[166:169], v[208:211], v[68:71]
	v_mfma_f32_16x16x32_bf16 v[64:67], v[174:177], v[208:211], v[64:67]
	v_mfma_f32_16x16x32_bf16 v[108:111], v[170:173], v[188:191], v[108:111]
	v_mfma_f32_16x16x32_bf16 v[104:107], v[178:181], v[188:191], v[104:107]
	v_mfma_f32_16x16x32_bf16 v[92:95], v[170:173], v[196:199], v[92:95]
	v_mfma_f32_16x16x32_bf16 v[88:91], v[178:181], v[196:199], v[88:91]
	v_mfma_f32_16x16x32_bf16 v[76:79], v[170:173], v[204:207], v[76:79]
	v_mfma_f32_16x16x32_bf16 v[72:75], v[178:181], v[204:207], v[72:75]
	v_mfma_f32_16x16x32_bf16 v[68:71], v[170:173], v[212:215], v[68:71]
	v_mfma_f32_16x16x32_bf16 v[64:67], v[178:181], v[212:215], v[64:67]
	s_setprio 0
	s_barrier
	s_add_i32 s60, s47, s38
	v_lshl_add_u64 v[216:217], s[28:29], 0, v[130:131]
	s_mov_b32 m0, s60
	ds_read_b128 v[184:187], v149 offset:16384
	ds_read_b128 v[188:191], v149 offset:17408
	ds_read_b128 v[192:195], v149 offset:18432
	ds_read_b128 v[196:199], v149 offset:19456
	ds_read_b128 v[200:203], v149 offset:20480
	ds_read_b128 v[204:207], v149 offset:21504
	ds_read_b128 v[208:211], v149 offset:22528
	ds_read_b128 v[212:215], v149 offset:23552
	global_load_lds_dwordx4 v[216:217], off
	s_add_i32 m0, s60, 0x2000
	s_add_u32 s60, s28, 0x80000
	v_lshl_add_u64 v[218:219], s[28:29], 0, v[134:135]
	s_addc_u32 s61, s29, 0
	s_add_i32 s62, s48, s38
	global_load_lds_dwordx4 v[218:219], off
	s_mov_b32 m0, s62
	v_lshl_add_u64 v[222:223], s[30:31], 0, v[132:133]
	global_load_lds_dwordx4 v130, s[60:61]
	s_add_i32 m0, s62, 0x2000
	s_nop 0
	global_load_lds_dwordx4 v134, s[60:61]
	v_lshl_add_u64 v[220:221], s[30:31], 0, v[128:129]
	s_mov_b32 m0, s39
	s_nop 0
	global_load_lds_dwordx4 v[220:221], off
	s_mov_b32 m0, s40
	s_nop 0
	global_load_lds_dwordx4 v[222:223], off
	s_waitcnt vmcnt(8) lgkmcnt(0)
	s_barrier
	s_setprio 1
	v_mfma_f32_16x16x32_bf16 v[60:63], v[150:153], v[184:187], v[60:63]
	v_mfma_f32_16x16x32_bf16 v[56:59], v[158:161], v[184:187], v[56:59]
	v_mfma_f32_16x16x32_bf16 v[52:55], v[150:153], v[192:195], v[52:55]
	v_mfma_f32_16x16x32_bf16 v[48:51], v[158:161], v[192:195], v[48:51]
	v_mfma_f32_16x16x32_bf16 v[36:39], v[150:153], v[200:203], v[36:39]
	v_mfma_f32_16x16x32_bf16 v[32:35], v[158:161], v[200:203], v[32:35]
	v_mfma_f32_16x16x32_bf16 v[20:23], v[150:153], v[208:211], v[20:23]
	v_mfma_f32_16x16x32_bf16 v[16:19], v[158:161], v[208:211], v[16:19]
	v_mfma_f32_16x16x32_bf16 v[60:63], v[154:157], v[188:191], v[60:63]
	v_mfma_f32_16x16x32_bf16 v[56:59], v[162:165], v[188:191], v[56:59]
	v_mfma_f32_16x16x32_bf16 v[52:55], v[154:157], v[196:199], v[52:55]
	v_mfma_f32_16x16x32_bf16 v[48:51], v[162:165], v[196:199], v[48:51]
	v_mfma_f32_16x16x32_bf16 v[36:39], v[154:157], v[204:207], v[36:39]
	v_mfma_f32_16x16x32_bf16 v[32:35], v[162:165], v[204:207], v[32:35]
	v_mfma_f32_16x16x32_bf16 v[20:23], v[154:157], v[212:215], v[20:23]
	v_mfma_f32_16x16x32_bf16 v[16:19], v[162:165], v[212:215], v[16:19]
	v_mfma_f32_16x16x32_bf16 v[44:47], v[166:169], v[184:187], v[44:47]
	v_mfma_f32_16x16x32_bf16 v[40:43], v[174:177], v[184:187], v[40:43]
	v_mfma_f32_16x16x32_bf16 v[28:31], v[166:169], v[192:195], v[28:31]
	v_mfma_f32_16x16x32_bf16 v[24:27], v[174:177], v[192:195], v[24:27]
	v_mfma_f32_16x16x32_bf16 v[12:15], v[166:169], v[200:203], v[12:15]
	v_mfma_f32_16x16x32_bf16 v[8:11], v[174:177], v[200:203], v[8:11]
	v_mfma_f32_16x16x32_bf16 v[4:7], v[166:169], v[208:211], v[4:7]
	v_mfma_f32_16x16x32_bf16 v[0:3], v[174:177], v[208:211], v[0:3]
	v_mfma_f32_16x16x32_bf16 v[44:47], v[170:173], v[188:191], v[44:47]
	v_mfma_f32_16x16x32_bf16 v[40:43], v[178:181], v[188:191], v[40:43]
	v_mfma_f32_16x16x32_bf16 v[28:31], v[170:173], v[196:199], v[28:31]
	v_mfma_f32_16x16x32_bf16 v[24:27], v[178:181], v[196:199], v[24:27]
	v_mfma_f32_16x16x32_bf16 v[12:15], v[170:173], v[204:207], v[12:15]
	v_mfma_f32_16x16x32_bf16 v[8:11], v[178:181], v[204:207], v[8:11]
	v_mfma_f32_16x16x32_bf16 v[4:7], v[170:173], v[212:215], v[4:7]
	v_mfma_f32_16x16x32_bf16 v[0:3], v[178:181], v[212:215], v[0:3]
	s_setprio 0
	s_barrier
	s_add_i32 s60, 0, 0x18000
	s_add_i32 s61, 0, 0x1c000
	v_add_u32_e32 v162, s60, v145
	v_add_u32_e32 v178, s61, v145
	ds_read_b128 v[150:153], v162
	ds_read_b128 v[154:157], v162 offset:1024
	ds_read_b128 v[158:161], v162 offset:2048
	ds_read_b128 v[162:165], v162 offset:3072
	ds_read_b128 v[166:169], v178
	ds_read_b128 v[170:173], v178 offset:1024
	ds_read_b128 v[174:177], v178 offset:2048
	ds_read_b128 v[178:181], v178 offset:3072
	s_add_u32 s30, s30, 0x160000
	s_addc_u32 s31, s31, 0
	s_mov_b32 m0, s41
	ds_read_b128 v[184:187], v149 offset:32768
	ds_read_b128 v[188:191], v149 offset:33792
	ds_read_b128 v[192:195], v149 offset:34816
	ds_read_b128 v[196:199], v149 offset:35840
	ds_read_b128 v[200:203], v149 offset:36864
	ds_read_b128 v[204:207], v149 offset:37888
	ds_read_b128 v[208:211], v149 offset:38912
	ds_read_b128 v[212:215], v149 offset:39936
	global_load_lds_dwordx4 v128, s[30:31]
	s_mov_b32 m0, s42
	s_nop 0
	global_load_lds_dwordx4 v132, s[30:31]
	s_waitcnt vmcnt(8) lgkmcnt(0)
	s_barrier
	s_setprio 1
	v_mfma_f32_16x16x32_bf16 v[124:127], v[150:153], v[184:187], v[124:127]
	v_mfma_f32_16x16x32_bf16 v[120:123], v[158:161], v[184:187], v[120:123]
	v_mfma_f32_16x16x32_bf16 v[116:119], v[150:153], v[192:195], v[116:119]
	v_mfma_f32_16x16x32_bf16 v[112:115], v[158:161], v[192:195], v[112:115]
	v_mfma_f32_16x16x32_bf16 v[100:103], v[150:153], v[200:203], v[100:103]
	v_mfma_f32_16x16x32_bf16 v[96:99], v[158:161], v[200:203], v[96:99]
	v_mfma_f32_16x16x32_bf16 v[84:87], v[150:153], v[208:211], v[84:87]
	v_mfma_f32_16x16x32_bf16 v[80:83], v[158:161], v[208:211], v[80:83]
	v_mfma_f32_16x16x32_bf16 v[124:127], v[154:157], v[188:191], v[124:127]
	v_mfma_f32_16x16x32_bf16 v[120:123], v[162:165], v[188:191], v[120:123]
	v_mfma_f32_16x16x32_bf16 v[116:119], v[154:157], v[196:199], v[116:119]
	v_mfma_f32_16x16x32_bf16 v[112:115], v[162:165], v[196:199], v[112:115]
	v_mfma_f32_16x16x32_bf16 v[100:103], v[154:157], v[204:207], v[100:103]
	v_mfma_f32_16x16x32_bf16 v[96:99], v[162:165], v[204:207], v[96:99]
	v_mfma_f32_16x16x32_bf16 v[84:87], v[154:157], v[212:215], v[84:87]
	v_mfma_f32_16x16x32_bf16 v[80:83], v[162:165], v[212:215], v[80:83]
	v_mfma_f32_16x16x32_bf16 v[108:111], v[166:169], v[184:187], v[108:111]
	v_mfma_f32_16x16x32_bf16 v[104:107], v[174:177], v[184:187], v[104:107]
	v_mfma_f32_16x16x32_bf16 v[92:95], v[166:169], v[192:195], v[92:95]
	v_mfma_f32_16x16x32_bf16 v[88:91], v[174:177], v[192:195], v[88:91]
	v_mfma_f32_16x16x32_bf16 v[76:79], v[166:169], v[200:203], v[76:79]
	v_mfma_f32_16x16x32_bf16 v[72:75], v[174:177], v[200:203], v[72:75]
	v_mfma_f32_16x16x32_bf16 v[68:71], v[166:169], v[208:211], v[68:71]
	v_mfma_f32_16x16x32_bf16 v[64:67], v[174:177], v[208:211], v[64:67]
	v_mfma_f32_16x16x32_bf16 v[108:111], v[170:173], v[188:191], v[108:111]
	v_mfma_f32_16x16x32_bf16 v[104:107], v[178:181], v[188:191], v[104:107]
	v_mfma_f32_16x16x32_bf16 v[92:95], v[170:173], v[196:199], v[92:95]
	v_mfma_f32_16x16x32_bf16 v[88:91], v[178:181], v[196:199], v[88:91]
	v_mfma_f32_16x16x32_bf16 v[76:79], v[170:173], v[204:207], v[76:79]
	v_mfma_f32_16x16x32_bf16 v[72:75], v[178:181], v[204:207], v[72:75]
	v_mfma_f32_16x16x32_bf16 v[68:71], v[170:173], v[212:215], v[68:71]
	v_mfma_f32_16x16x32_bf16 v[64:67], v[178:181], v[212:215], v[64:67]
	s_setprio 0
	s_barrier
	s_add_i32 s30, s60, s38
	v_lshl_add_u64 v[216:217], v[216:217], 0, s[10:11]
	s_mov_b32 m0, s30
	ds_read_b128 v[184:187], v149 offset:49152
	ds_read_b128 v[188:191], v149 offset:50176
	ds_read_b128 v[192:195], v149 offset:51200
	ds_read_b128 v[196:199], v149 offset:52224
	ds_read_b128 v[200:203], v149 offset:53248
	ds_read_b128 v[204:207], v149 offset:54272
	ds_read_b128 v[208:211], v149 offset:55296
	ds_read_b128 v[212:215], v149 offset:56320
	global_load_lds_dwordx4 v[216:217], off
	s_add_i32 m0, s30, 0x2000
	s_add_u32 s28, s28, 0x80080
	v_lshl_add_u64 v[216:217], v[218:219], 0, s[10:11]
	s_addc_u32 s29, s29, 0
	s_add_i32 s30, s61, s38
	global_load_lds_dwordx4 v[216:217], off
	s_mov_b32 m0, s30
	s_nop 0
	global_load_lds_dwordx4 v130, s[28:29]
	s_add_i32 m0, s30, 0x2000
	s_nop 0
	global_load_lds_dwordx4 v134, s[28:29]
	v_lshl_add_u64 v[216:217], v[220:221], 0, s[10:11]
	s_mov_b32 m0, s45
	s_nop 0
	global_load_lds_dwordx4 v[216:217], off
	v_lshl_add_u64 v[216:217], v[222:223], 0, s[10:11]
	s_mov_b32 m0, s46
	s_nop 0
	global_load_lds_dwordx4 v[216:217], off
	s_waitcnt vmcnt(8) lgkmcnt(0)
	s_barrier
	s_setprio 1
	v_mfma_f32_16x16x32_bf16 v[60:63], v[150:153], v[184:187], v[60:63]
	v_mfma_f32_16x16x32_bf16 v[56:59], v[158:161], v[184:187], v[56:59]
	v_mfma_f32_16x16x32_bf16 v[52:55], v[150:153], v[192:195], v[52:55]
	v_mfma_f32_16x16x32_bf16 v[48:51], v[158:161], v[192:195], v[48:51]
	v_mfma_f32_16x16x32_bf16 v[36:39], v[150:153], v[200:203], v[36:39]
	v_mfma_f32_16x16x32_bf16 v[32:35], v[158:161], v[200:203], v[32:35]
	v_mfma_f32_16x16x32_bf16 v[20:23], v[150:153], v[208:211], v[20:23]
	v_mfma_f32_16x16x32_bf16 v[16:19], v[158:161], v[208:211], v[16:19]
	v_mfma_f32_16x16x32_bf16 v[60:63], v[154:157], v[188:191], v[60:63]
	v_mfma_f32_16x16x32_bf16 v[56:59], v[162:165], v[188:191], v[56:59]
	v_mfma_f32_16x16x32_bf16 v[52:55], v[154:157], v[196:199], v[52:55]
	v_mfma_f32_16x16x32_bf16 v[48:51], v[162:165], v[196:199], v[48:51]
	v_mfma_f32_16x16x32_bf16 v[36:39], v[154:157], v[204:207], v[36:39]
	v_mfma_f32_16x16x32_bf16 v[32:35], v[162:165], v[204:207], v[32:35]
	v_mfma_f32_16x16x32_bf16 v[20:23], v[154:157], v[212:215], v[20:23]
	v_mfma_f32_16x16x32_bf16 v[16:19], v[162:165], v[212:215], v[16:19]
	v_mfma_f32_16x16x32_bf16 v[44:47], v[166:169], v[184:187], v[44:47]
	v_mfma_f32_16x16x32_bf16 v[40:43], v[174:177], v[184:187], v[40:43]
	v_mfma_f32_16x16x32_bf16 v[28:31], v[166:169], v[192:195], v[28:31]
	v_mfma_f32_16x16x32_bf16 v[24:27], v[174:177], v[192:195], v[24:27]
	v_mfma_f32_16x16x32_bf16 v[12:15], v[166:169], v[200:203], v[12:15]
	v_mfma_f32_16x16x32_bf16 v[8:11], v[174:177], v[200:203], v[8:11]
	v_mfma_f32_16x16x32_bf16 v[4:7], v[166:169], v[208:211], v[4:7]
	v_mfma_f32_16x16x32_bf16 v[0:3], v[174:177], v[208:211], v[0:3]
	v_mfma_f32_16x16x32_bf16 v[44:47], v[170:173], v[188:191], v[44:47]
	v_mfma_f32_16x16x32_bf16 v[40:43], v[178:181], v[188:191], v[40:43]
	v_mfma_f32_16x16x32_bf16 v[28:31], v[170:173], v[196:199], v[28:31]
	v_mfma_f32_16x16x32_bf16 v[24:27], v[178:181], v[196:199], v[24:27]
	v_mfma_f32_16x16x32_bf16 v[12:15], v[170:173], v[204:207], v[12:15]
	v_mfma_f32_16x16x32_bf16 v[8:11], v[178:181], v[204:207], v[8:11]
	v_mfma_f32_16x16x32_bf16 v[4:7], v[170:173], v[212:215], v[4:7]
	v_mfma_f32_16x16x32_bf16 v[0:3], v[178:181], v[212:215], v[0:3]
	s_setprio 0
	s_barrier
	s_add_i32 s59, s59, 2
	s_add_u32 s4, s4, 0x100
	s_addc_u32 s5, s5, 0
	s_add_u32 s57, s57, 0x100
	s_addc_u32 s58, s58, 0
	s_cmp_gt_u32 s59, 29
	s_cbranch_scc0 .LBB0_1274
	s_and_b64 vcc, exec, s[12:13]
	s_cbranch_vccz .LBB0_1277
	s_barrier
